# strategy 4 mirror: static s_setprio 1 for waves 0-3 across the P3 attention queue
# baseline (speedup 1.0000x reference)
; #define LAS __attribute__((address_space(3)))
; #define OPQ_WS() argp_t ap = (argp_t)__builtin_amdgcn_kernarg_segment_ptr(); asm volatile("" : "+s"(ap)); unsigned char* ws = ap->ws
; __device__ __forceinline__ int opaque_tid() {
;     const unsigned hw = __builtin_amdgcn_s_getreg((5 << 11) | 4) & 63u;
;     const int w = __builtin_amdgcn_readfirstlane(*(volatile LAS int*)(uintptr_t)(LDS_WTAB + hw * 4));
;     unsigned z = 0u; asm volatile("" : "+v"(z));
;     const int lane = (int)__builtin_amdgcn_mbcnt_hi(~0u, __builtin_amdgcn_mbcnt_lo(~0u, z));
;     return (w << 6) | lane;
;     ...
;     if constexpr (PH == 3) {
;         {
;             OPQ_WS();
;             for (int rep = 0; rep < REP_A01; ++rep) {
;             unsigned* ctr = ctrl + L * 32 + 2 + 4 * rep;
;             __syncthreads();
;             for (int it = bx;;) {
;                 if (it >= 704) break;
;                 const int qb = 15 - it / 44, w = it % 44;
;                 if (w < 24) { const int b = w / 6, h = w % 6;
;                     att::AttnPtrs A{QMLA + h * 192, NUQ, KMLA + h * 128, 768, KROPE, VMLA + h * 128, 768, GATE + h * 128, GATE + h * 128, nullptr, 0.f, 0.f, (const float*)TAB};
.LBB0_1164:
	s_or_b64 exec, exec, s[0:1]
	v_readlane_b32 s2, v254, 19
	v_readlane_b32 s3, v254, 20
	s_mov_b64 s[0:1], s[86:87]
	s_andn2_b64 vcc, exec, s[2:3]
	s_waitcnt lgkmcnt(0)
	s_barrier
	s_barrier
	s_cbranch_vccnz .LBB0_1205
	s_getreg_b32 s4, hwreg(HW_REG_HW_ID, 0, 6)
	s_lshl_b32 s4, s4, 2
	s_and_b32 s4, s4, 0xfc
	s_add_i32 s4, s4, 0x20040
	v_mov_b32_e32 v0, s4
	ds_read_b32 v0, v0
	s_waitcnt lgkmcnt(0)
	v_readfirstlane_b32 s4, v0
	s_nop 3
	s_cmp_ge_u32 s4, 4
	s_cbranch_scc1 .Lp3_prio_done
	s_setprio 1
